# mLSTM latent chain: software-pipeline the 16 serialized ds_read->MFMA of the C-state update (counted lgkmcnt, spare VGPRs)
# baseline (speedup 1.0000x reference)
.LBB0_615:
	v_add_u32_e32 v66, v93, v99
	ds_read_b128 v[58:61], v80 offset:53248
	ds_read_b128 v[158:161], v66 offset:34816
	ds_read_b128 v[162:165], v66 offset:37120
	ds_read_b128 v[166:169], v66 offset:39424
	ds_read_b128 v[170:173], v66 offset:41728
	ds_read_b128 v[174:177], v66 offset:44032
	ds_read_b128 v[180:183], v66 offset:46336
	ds_read_b128 v[184:187], v66 offset:48640
	ds_read_b128 v[188:191], v66 offset:50944
	ds_read_b128 v[192:195], v80 offset:53312
	v_pk_mul_f32 v[4:5], v[4:5], v[78:79] op_sel_hi:[1,0]
	v_pk_mul_f32 v[2:3], v[2:3], v[78:79] op_sel_hi:[1,0]
	v_pk_mul_f32 v[8:9], v[8:9], v[78:79] op_sel_hi:[1,0]
	v_pk_mul_f32 v[6:7], v[6:7], v[78:79] op_sel_hi:[1,0]
	v_pk_mul_f32 v[12:13], v[12:13], v[78:79] op_sel_hi:[1,0]
	v_pk_mul_f32 v[10:11], v[10:11], v[78:79] op_sel_hi:[1,0]
	v_pk_mul_f32 v[16:17], v[16:17], v[78:79] op_sel_hi:[1,0]
	v_pk_mul_f32 v[14:15], v[14:15], v[78:79] op_sel_hi:[1,0]
	v_pk_mul_f32 v[20:21], v[20:21], v[78:79] op_sel_hi:[1,0]
	v_pk_mul_f32 v[18:19], v[18:19], v[78:79] op_sel_hi:[1,0]
	v_pk_mul_f32 v[24:25], v[24:25], v[78:79] op_sel_hi:[1,0]
	v_pk_mul_f32 v[22:23], v[22:23], v[78:79] op_sel_hi:[1,0]
	v_pk_mul_f32 v[28:29], v[28:29], v[78:79] op_sel_hi:[1,0]
	v_pk_mul_f32 v[26:27], v[26:27], v[78:79] op_sel_hi:[1,0]
	v_pk_mul_f32 v[32:33], v[32:33], v[78:79] op_sel_hi:[1,0]
	v_pk_mul_f32 v[30:31], v[30:31], v[78:79] op_sel_hi:[1,0]
	v_subrev_u32_e32 v101, 64, v101
	v_subrev_u32_e32 v102, 64, v102
	v_subrev_u32_e32 v103, 64, v103
	v_subrev_u32_e32 v104, 64, v104
	v_subrev_u32_e32 v105, 64, v105
	v_subrev_u32_e32 v106, 64, v106
	v_subrev_u32_e32 v107, 64, v107
	v_subrev_u32_e32 v108, 64, v108
	v_subrev_u32_e32 v109, 64, v109
	v_add_u32_e32 v110, 64, v110
	v_add_u32_e32 v111, 64, v111
	v_add_u32_e32 v136, 64, v136
	v_add_u32_e32 v112, 64, v112
	v_add_u32_e32 v113, 64, v113
	v_add_u32_e32 v114, 64, v114
	v_add_u32_e32 v115, 64, v115
	v_add_u32_e32 v116, 64, v116
	v_add_u32_e32 v117, 64, v117
	v_subrev_u32_e32 v118, 64, v118
	v_subrev_u32_e32 v119, 64, v119
	v_add_u32_e32 v120, 64, v120
	v_subrev_u32_e32 v121, 64, v121
	v_add_u32_e32 v122, 64, v122
	v_add_u32_e32 v123, 64, v123
	s_waitcnt lgkmcnt(8)
	v_mfma_f32_16x16x32_bf16 v[2:5], v[158:161], v[58:61], v[2:5]
	ds_read_b128 v[196:199], v66 offset:34880
	s_waitcnt lgkmcnt(8)
	v_mfma_f32_16x16x32_bf16 v[6:9], v[162:165], v[58:61], v[6:9]
	ds_read_b128 v[200:203], v66 offset:37184
	s_waitcnt lgkmcnt(8)
	v_mfma_f32_16x16x32_bf16 v[10:13], v[166:169], v[58:61], v[10:13]
	ds_read_b128 v[204:207], v66 offset:39488
	s_waitcnt lgkmcnt(8)
	v_mfma_f32_16x16x32_bf16 v[14:17], v[170:173], v[58:61], v[14:17]
	ds_read_b128 v[208:211], v66 offset:41792
	s_waitcnt lgkmcnt(8)
	v_mfma_f32_16x16x32_bf16 v[18:21], v[174:177], v[58:61], v[18:21]
	ds_read_b128 v[212:215], v66 offset:44096
	s_waitcnt lgkmcnt(8)
	v_mfma_f32_16x16x32_bf16 v[22:25], v[180:183], v[58:61], v[22:25]
	ds_read_b128 v[216:219], v66 offset:46400
	s_waitcnt lgkmcnt(8)
	v_mfma_f32_16x16x32_bf16 v[26:29], v[184:187], v[58:61], v[26:29]
	ds_read_b128 v[220:223], v66 offset:48704
	s_waitcnt lgkmcnt(8)
	v_mfma_f32_16x16x32_bf16 v[30:33], v[188:191], v[58:61], v[30:33]
	ds_read_b128 v[224:227], v66 offset:51008
	v_mov_b32_e32 v228, s51
	ds_read_b32 v228, v228 offset:764
	s_waitcnt lgkmcnt(8)
	v_mfma_f32_16x16x32_bf16 v[2:5], v[196:199], v[192:195], v[2:5]
	s_waitcnt lgkmcnt(7)
	v_mfma_f32_16x16x32_bf16 v[6:9], v[200:203], v[192:195], v[6:9]
	s_waitcnt lgkmcnt(6)
	v_mfma_f32_16x16x32_bf16 v[10:13], v[204:207], v[192:195], v[10:13]
	s_waitcnt lgkmcnt(5)
	v_mfma_f32_16x16x32_bf16 v[14:17], v[208:211], v[192:195], v[14:17]
	s_waitcnt lgkmcnt(4)
	v_mfma_f32_16x16x32_bf16 v[18:21], v[212:215], v[192:195], v[18:21]
	s_waitcnt lgkmcnt(3)
	v_mfma_f32_16x16x32_bf16 v[22:25], v[216:219], v[192:195], v[22:25]
	s_waitcnt lgkmcnt(2)
	v_mfma_f32_16x16x32_bf16 v[26:29], v[220:223], v[192:195], v[26:29]
	s_waitcnt lgkmcnt(1)
	v_mfma_f32_16x16x32_bf16 v[30:33], v[224:227], v[192:195], v[30:33]
	s_cmp_lg_u32 s88, s50
	s_mov_b32 s84, s50
	s_waitcnt lgkmcnt(0)
	v_add_f32_e32 v64, v137, v228
	s_cbranch_scc0 .LBB0_648
